# v53 + SGPR-base LDS-DMA addressing in the up and W_in K-loops
# speedup vs baseline: 1.0401x; 1.0026x over previous
.LBB0_159:
	s_add_u32 s0, s22, 0xfff80080
	s_addc_u32 s1, s23, -1
	s_add_i32 s51, 0, 0x10000
	s_cmp_eq_u32 s50, 28
	s_cselect_b32 s27, s15, s1
	s_cselect_b32 s26, s46, s0
	v_add_u32_e32 v140, s51, v143
	s_cselect_b32 s25, s13, s49
	s_cselect_b32 s24, s47, s48
	s_add_i32 s0, 0, 0x14000
	ds_read_b128 v[146:149], v140
	ds_read_b128 v[150:153], v140 offset:1024
	ds_read_b128 v[154:157], v140 offset:2048
	ds_read_b128 v[158:161], v140 offset:3072
	v_add_u32_e32 v140, s0, v143
	ds_read_b128 v[162:165], v140
	ds_read_b128 v[166:169], v140 offset:1024
	ds_read_b128 v[170:173], v140 offset:2048
	ds_read_b128 v[174:177], v140 offset:3072
	s_add_i32 m0, s35, 0xc000
	ds_read_b128 v[178:181], v144
	ds_read_b128 v[182:185], v144 offset:1024
	ds_read_b128 v[192:195], v144 offset:2048
	ds_read_b128 v[196:199], v144 offset:3072
	ds_read_b128 v[200:203], v144 offset:4096
	ds_read_b128 v[204:207], v144 offset:5120
	ds_read_b128 v[208:211], v144 offset:6144
	ds_read_b128 v[212:215], v144 offset:7168
	global_load_lds_dwordx4 v136, s[22:23]
	s_add_i32 m0, s35, 0xe000
	s_nop 0
	global_load_lds_dwordx4 v138, s[22:23]
	s_waitcnt vmcnt(8)
	s_waitcnt lgkmcnt(0)
	s_setprio 1
	s_barrier

	v_mfma_f32_16x16x32_bf16 v[126:129], v[146:149], v[178:181], v[126:129]
	v_mfma_f32_16x16x32_bf16 v[126:129], v[150:153], v[182:185], v[126:129]
	v_mfma_f32_16x16x32_bf16 v[118:121], v[158:161], v[182:185], v[118:121]
	v_mfma_f32_16x16x32_bf16 v[118:121], v[154:157], v[178:181], v[118:121]
	v_mfma_f32_16x16x32_bf16 v[102:105], v[154:157], v[192:195], v[102:105]
	v_mfma_f32_16x16x32_bf16 v[102:105], v[158:161], v[196:199], v[102:105]
	v_mfma_f32_16x16x32_bf16 v[110:113], v[150:153], v[196:199], v[110:113]
	v_mfma_f32_16x16x32_bf16 v[110:113], v[146:149], v[192:195], v[110:113]
	v_mfma_f32_16x16x32_bf16 v[94:97], v[146:149], v[200:203], v[94:97]
	v_mfma_f32_16x16x32_bf16 v[94:97], v[150:153], v[204:207], v[94:97]
	v_mfma_f32_16x16x32_bf16 v[86:89], v[158:161], v[204:207], v[86:89]
	v_mfma_f32_16x16x32_bf16 v[86:89], v[154:157], v[200:203], v[86:89]
	v_mfma_f32_16x16x32_bf16 v[70:73], v[154:157], v[208:211], v[70:73]
	v_mfma_f32_16x16x32_bf16 v[70:73], v[158:161], v[212:215], v[70:73]
	v_mfma_f32_16x16x32_bf16 v[78:81], v[150:153], v[212:215], v[78:81]
	v_mfma_f32_16x16x32_bf16 v[78:81], v[146:149], v[208:211], v[78:81]


	v_mfma_f32_16x16x32_bf16 v[122:125], v[162:165], v[178:181], v[122:125]
	v_mfma_f32_16x16x32_bf16 v[122:125], v[166:169], v[182:185], v[122:125]
	v_mfma_f32_16x16x32_bf16 v[114:117], v[174:177], v[182:185], v[114:117]
	v_mfma_f32_16x16x32_bf16 v[114:117], v[170:173], v[178:181], v[114:117]
	v_mfma_f32_16x16x32_bf16 v[98:101], v[170:173], v[192:195], v[98:101]
	v_mfma_f32_16x16x32_bf16 v[98:101], v[174:177], v[196:199], v[98:101]
	v_mfma_f32_16x16x32_bf16 v[106:109], v[166:169], v[196:199], v[106:109]
	v_mfma_f32_16x16x32_bf16 v[106:109], v[162:165], v[192:195], v[106:109]
	v_mfma_f32_16x16x32_bf16 v[90:93], v[162:165], v[200:203], v[90:93]
	v_mfma_f32_16x16x32_bf16 v[90:93], v[166:169], v[204:207], v[90:93]
	v_mfma_f32_16x16x32_bf16 v[82:85], v[174:177], v[204:207], v[82:85]
	v_mfma_f32_16x16x32_bf16 v[82:85], v[170:173], v[200:203], v[82:85]
	v_mfma_f32_16x16x32_bf16 v[66:69], v[170:173], v[208:211], v[66:69]
	v_mfma_f32_16x16x32_bf16 v[66:69], v[174:177], v[212:215], v[66:69]
	v_mfma_f32_16x16x32_bf16 v[74:77], v[166:169], v[212:215], v[74:77]
	v_mfma_f32_16x16x32_bf16 v[74:77], v[162:165], v[208:211], v[74:77]
	s_barrier
	s_setprio 0
	s_add_i32 s1, s51, s31
	s_mov_b32 m0, s1
	ds_read_b128 v[178:181], v144 offset:16384
	ds_read_b128 v[182:185], v144 offset:17408
	ds_read_b128 v[192:195], v144 offset:18432
	ds_read_b128 v[196:199], v144 offset:19456
	ds_read_b128 v[200:203], v144 offset:20480
	ds_read_b128 v[204:207], v144 offset:21504
	ds_read_b128 v[208:211], v144 offset:22528
	ds_read_b128 v[212:215], v144 offset:23552
	global_load_lds_dwordx4 v186, s[24:25]
	s_add_i32 m0, s1, 0x2000
	s_add_u32 s52, s24, 0x80000
	s_addc_u32 s53, s25, 0
	s_add_i32 s0, s0, s31
	global_load_lds_dwordx4 v130, s[24:25]
	s_mov_b32 m0, s0
	s_nop 0
	global_load_lds_dwordx4 v186, s[52:53]
	s_add_i32 m0, s0, 0x2000
	s_nop 0
	global_load_lds_dwordx4 v130, s[52:53]
	s_mov_b32 m0, s35
	s_nop 0
	global_load_lds_dwordx4 v134, s[26:27]
	s_mov_b32 m0, s36
	s_nop 0
	global_load_lds_dwordx4 v132, s[26:27]
	s_waitcnt vmcnt(8)
	s_waitcnt lgkmcnt(0)
	s_setprio 1
	s_barrier

	v_mfma_f32_16x16x32_bf16 v[62:65], v[146:149], v[178:181], v[62:65]
	v_mfma_f32_16x16x32_bf16 v[62:65], v[150:153], v[182:185], v[62:65]
	v_mfma_f32_16x16x32_bf16 v[54:57], v[158:161], v[182:185], v[54:57]
	v_mfma_f32_16x16x32_bf16 v[54:57], v[154:157], v[178:181], v[54:57]
	v_mfma_f32_16x16x32_bf16 v[38:41], v[154:157], v[192:195], v[38:41]
	v_mfma_f32_16x16x32_bf16 v[38:41], v[158:161], v[196:199], v[38:41]
	v_mfma_f32_16x16x32_bf16 v[46:49], v[150:153], v[196:199], v[46:49]
	v_mfma_f32_16x16x32_bf16 v[46:49], v[146:149], v[192:195], v[46:49]
	v_mfma_f32_16x16x32_bf16 v[30:33], v[146:149], v[200:203], v[30:33]
	v_mfma_f32_16x16x32_bf16 v[30:33], v[150:153], v[204:207], v[30:33]
	v_mfma_f32_16x16x32_bf16 v[22:25], v[158:161], v[204:207], v[22:25]
	v_mfma_f32_16x16x32_bf16 v[22:25], v[154:157], v[200:203], v[22:25]
	v_mfma_f32_16x16x32_bf16 v[6:9], v[154:157], v[208:211], v[6:9]
	v_mfma_f32_16x16x32_bf16 v[6:9], v[158:161], v[212:215], v[6:9]
	v_mfma_f32_16x16x32_bf16 v[14:17], v[150:153], v[212:215], v[14:17]
	v_mfma_f32_16x16x32_bf16 v[14:17], v[146:149], v[208:211], v[14:17]


	v_mfma_f32_16x16x32_bf16 v[58:61], v[162:165], v[178:181], v[58:61]
	v_mfma_f32_16x16x32_bf16 v[58:61], v[166:169], v[182:185], v[58:61]
	v_mfma_f32_16x16x32_bf16 v[50:53], v[174:177], v[182:185], v[50:53]
	v_mfma_f32_16x16x32_bf16 v[50:53], v[170:173], v[178:181], v[50:53]
	v_mfma_f32_16x16x32_bf16 v[34:37], v[170:173], v[192:195], v[34:37]
	v_mfma_f32_16x16x32_bf16 v[34:37], v[174:177], v[196:199], v[34:37]
	v_mfma_f32_16x16x32_bf16 v[42:45], v[166:169], v[196:199], v[42:45]
	v_mfma_f32_16x16x32_bf16 v[42:45], v[162:165], v[192:195], v[42:45]
	v_mfma_f32_16x16x32_bf16 v[26:29], v[162:165], v[200:203], v[26:29]
	v_mfma_f32_16x16x32_bf16 v[26:29], v[166:169], v[204:207], v[26:29]
	v_mfma_f32_16x16x32_bf16 v[18:21], v[174:177], v[204:207], v[18:21]
	v_mfma_f32_16x16x32_bf16 v[18:21], v[170:173], v[200:203], v[18:21]
	v_mfma_f32_16x16x32_bf16 v[2:5], v[170:173], v[208:211], v[2:5]
	v_mfma_f32_16x16x32_bf16 v[2:5], v[174:177], v[212:215], v[2:5]
	v_mfma_f32_16x16x32_bf16 v[10:13], v[166:169], v[212:215], v[10:13]
	v_mfma_f32_16x16x32_bf16 v[10:13], v[162:165], v[208:211], v[10:13]
	s_barrier
	s_setprio 0
	s_add_i32 s0, 0, 0x18000
	v_add_u32_e32 v145, s0, v143
	s_add_i32 s1, 0, 0x1c000
	ds_read_b128 v[146:149], v145
	ds_read_b128 v[150:153], v145 offset:1024
	ds_read_b128 v[154:157], v145 offset:2048
	ds_read_b128 v[158:161], v145 offset:3072
	v_add_u32_e32 v145, s1, v143
	ds_read_b128 v[162:165], v145
	ds_read_b128 v[166:169], v145 offset:1024
	ds_read_b128 v[170:173], v145 offset:2048
	ds_read_b128 v[174:177], v145 offset:3072
	s_add_u32 s26, s26, 0x80000
	s_addc_u32 s27, s27, 0
	s_mov_b32 m0, s37
	ds_read_b128 v[178:181], v144 offset:32768
	ds_read_b128 v[182:185], v144 offset:33792
	ds_read_b128 v[192:195], v144 offset:34816
	ds_read_b128 v[196:199], v144 offset:35840
	ds_read_b128 v[200:203], v144 offset:36864
	ds_read_b128 v[204:207], v144 offset:37888
	ds_read_b128 v[208:211], v144 offset:38912
	ds_read_b128 v[212:215], v144 offset:39936
	global_load_lds_dwordx4 v134, s[26:27]
	s_mov_b32 m0, s38
	s_nop 0
	global_load_lds_dwordx4 v132, s[26:27]
	s_waitcnt vmcnt(8)
	s_waitcnt lgkmcnt(0)
	s_setprio 1
	s_barrier

	v_mfma_f32_16x16x32_bf16 v[126:129], v[146:149], v[178:181], v[126:129]
	v_mfma_f32_16x16x32_bf16 v[126:129], v[150:153], v[182:185], v[126:129]
	v_mfma_f32_16x16x32_bf16 v[118:121], v[158:161], v[182:185], v[118:121]
	v_mfma_f32_16x16x32_bf16 v[118:121], v[154:157], v[178:181], v[118:121]
	v_mfma_f32_16x16x32_bf16 v[102:105], v[154:157], v[192:195], v[102:105]
	v_mfma_f32_16x16x32_bf16 v[102:105], v[158:161], v[196:199], v[102:105]
	v_mfma_f32_16x16x32_bf16 v[110:113], v[150:153], v[196:199], v[110:113]
	v_mfma_f32_16x16x32_bf16 v[110:113], v[146:149], v[192:195], v[110:113]
	v_mfma_f32_16x16x32_bf16 v[94:97], v[146:149], v[200:203], v[94:97]
	v_mfma_f32_16x16x32_bf16 v[94:97], v[150:153], v[204:207], v[94:97]
	v_mfma_f32_16x16x32_bf16 v[86:89], v[158:161], v[204:207], v[86:89]
	v_mfma_f32_16x16x32_bf16 v[86:89], v[154:157], v[200:203], v[86:89]
	v_mfma_f32_16x16x32_bf16 v[70:73], v[154:157], v[208:211], v[70:73]
	v_mfma_f32_16x16x32_bf16 v[70:73], v[158:161], v[212:215], v[70:73]
	v_mfma_f32_16x16x32_bf16 v[78:81], v[150:153], v[212:215], v[78:81]
	v_mfma_f32_16x16x32_bf16 v[78:81], v[146:149], v[208:211], v[78:81]


	v_mfma_f32_16x16x32_bf16 v[122:125], v[162:165], v[178:181], v[122:125]
	v_mfma_f32_16x16x32_bf16 v[122:125], v[166:169], v[182:185], v[122:125]
	v_mfma_f32_16x16x32_bf16 v[114:117], v[174:177], v[182:185], v[114:117]
	v_mfma_f32_16x16x32_bf16 v[114:117], v[170:173], v[178:181], v[114:117]
	v_mfma_f32_16x16x32_bf16 v[98:101], v[170:173], v[192:195], v[98:101]
	v_mfma_f32_16x16x32_bf16 v[98:101], v[174:177], v[196:199], v[98:101]
	v_mfma_f32_16x16x32_bf16 v[106:109], v[166:169], v[196:199], v[106:109]
	v_mfma_f32_16x16x32_bf16 v[106:109], v[162:165], v[192:195], v[106:109]
	v_mfma_f32_16x16x32_bf16 v[90:93], v[162:165], v[200:203], v[90:93]
	v_mfma_f32_16x16x32_bf16 v[90:93], v[166:169], v[204:207], v[90:93]
	v_mfma_f32_16x16x32_bf16 v[82:85], v[174:177], v[204:207], v[82:85]
	v_mfma_f32_16x16x32_bf16 v[82:85], v[170:173], v[200:203], v[82:85]
	v_mfma_f32_16x16x32_bf16 v[66:69], v[170:173], v[208:211], v[66:69]
	v_mfma_f32_16x16x32_bf16 v[66:69], v[174:177], v[212:215], v[66:69]
	v_mfma_f32_16x16x32_bf16 v[74:77], v[166:169], v[212:215], v[74:77]
	v_mfma_f32_16x16x32_bf16 v[74:77], v[162:165], v[208:211], v[74:77]
	s_barrier
	s_setprio 0
	s_add_i32 s0, s0, s31
	s_mov_b32 m0, s0
	ds_read_b128 v[178:181], v144 offset:49152
	ds_read_b128 v[182:185], v144 offset:50176
	ds_read_b128 v[192:195], v144 offset:51200
	ds_read_b128 v[196:199], v144 offset:52224
	ds_read_b128 v[200:203], v144 offset:53248
	ds_read_b128 v[204:207], v144 offset:54272
	ds_read_b128 v[208:211], v144 offset:55296
	ds_read_b128 v[212:215], v144 offset:56320
	s_add_u32 s100, s24, 0x80
	s_addc_u32 s101, s25, 0
	global_load_lds_dwordx4 v186, s[100:101]
	s_add_i32 m0, s0, 0x2000
	s_add_u32 s24, s24, 0x80080
	s_addc_u32 s25, s25, 0
	s_add_i32 s0, s1, s31
	s_add_u32 s100, s24, 0xfff80000
	s_addc_u32 s101, s25, -1
	global_load_lds_dwordx4 v130, s[100:101]
	s_mov_b32 m0, s0
	s_nop 0
	global_load_lds_dwordx4 v186, s[24:25]
	s_add_i32 m0, s0, 0x2000
	s_nop 0
	global_load_lds_dwordx4 v130, s[24:25]
	s_mov_b32 m0, s39
	s_nop 0
	s_add_u32 s100, s26, 0xfff80080
	s_addc_u32 s101, s27, -1
	global_load_lds_dwordx4 v134, s[100:101]
	s_mov_b32 m0, s40
	s_nop 0
	s_add_u32 s100, s26, 0xfff80080
	s_addc_u32 s101, s27, -1
	global_load_lds_dwordx4 v132, s[100:101]
	s_waitcnt vmcnt(8)
	s_waitcnt lgkmcnt(0)
	s_setprio 1
	s_barrier

	v_mfma_f32_16x16x32_bf16 v[62:65], v[146:149], v[178:181], v[62:65]
	v_mfma_f32_16x16x32_bf16 v[62:65], v[150:153], v[182:185], v[62:65]
	v_mfma_f32_16x16x32_bf16 v[54:57], v[158:161], v[182:185], v[54:57]
	v_mfma_f32_16x16x32_bf16 v[54:57], v[154:157], v[178:181], v[54:57]
	v_mfma_f32_16x16x32_bf16 v[38:41], v[154:157], v[192:195], v[38:41]
	v_mfma_f32_16x16x32_bf16 v[38:41], v[158:161], v[196:199], v[38:41]
	v_mfma_f32_16x16x32_bf16 v[46:49], v[150:153], v[196:199], v[46:49]
	v_mfma_f32_16x16x32_bf16 v[46:49], v[146:149], v[192:195], v[46:49]
	v_mfma_f32_16x16x32_bf16 v[30:33], v[146:149], v[200:203], v[30:33]
	v_mfma_f32_16x16x32_bf16 v[30:33], v[150:153], v[204:207], v[30:33]
	v_mfma_f32_16x16x32_bf16 v[22:25], v[158:161], v[204:207], v[22:25]
	v_mfma_f32_16x16x32_bf16 v[22:25], v[154:157], v[200:203], v[22:25]
	v_mfma_f32_16x16x32_bf16 v[6:9], v[154:157], v[208:211], v[6:9]
	v_mfma_f32_16x16x32_bf16 v[6:9], v[158:161], v[212:215], v[6:9]
	v_mfma_f32_16x16x32_bf16 v[14:17], v[150:153], v[212:215], v[14:17]
	v_mfma_f32_16x16x32_bf16 v[14:17], v[146:149], v[208:211], v[14:17]


	v_mfma_f32_16x16x32_bf16 v[58:61], v[162:165], v[178:181], v[58:61]
	v_mfma_f32_16x16x32_bf16 v[58:61], v[166:169], v[182:185], v[58:61]
	v_mfma_f32_16x16x32_bf16 v[50:53], v[174:177], v[182:185], v[50:53]
	v_mfma_f32_16x16x32_bf16 v[50:53], v[170:173], v[178:181], v[50:53]
	v_mfma_f32_16x16x32_bf16 v[34:37], v[170:173], v[192:195], v[34:37]
	v_mfma_f32_16x16x32_bf16 v[34:37], v[174:177], v[196:199], v[34:37]
	v_mfma_f32_16x16x32_bf16 v[42:45], v[166:169], v[196:199], v[42:45]
	v_mfma_f32_16x16x32_bf16 v[42:45], v[162:165], v[192:195], v[42:45]
	v_mfma_f32_16x16x32_bf16 v[26:29], v[162:165], v[200:203], v[26:29]
	v_mfma_f32_16x16x32_bf16 v[26:29], v[166:169], v[204:207], v[26:29]
	v_mfma_f32_16x16x32_bf16 v[18:21], v[174:177], v[204:207], v[18:21]
	v_mfma_f32_16x16x32_bf16 v[18:21], v[170:173], v[200:203], v[18:21]
	v_mfma_f32_16x16x32_bf16 v[2:5], v[170:173], v[208:211], v[2:5]
	v_mfma_f32_16x16x32_bf16 v[2:5], v[174:177], v[212:215], v[2:5]
	v_mfma_f32_16x16x32_bf16 v[10:13], v[166:169], v[212:215], v[10:13]
	v_mfma_f32_16x16x32_bf16 v[10:13], v[162:165], v[208:211], v[10:13]
	s_barrier
	s_setprio 0
	s_add_i32 s50, s50, 2
	s_add_u32 s22, s22, 0x100
	s_addc_u32 s23, s23, 0
	s_add_u32 s48, s48, 0x100
	s_addc_u32 s49, s49, 0
	s_cmp_gt_u32 s50, 29
	s_cbranch_scc0 .LBB0_159
	s_and_b64 vcc, exec, s[10:11]
	s_cbranch_vccz .LBB0_162
	s_barrier

.LBB0_443:
	s_add_u32 s0, s26, 0xfff80080
	s_addc_u32 s1, s27, -1
	s_add_i32 s56, 0, 0x10000
	s_cmp_eq_u32 s55, 28
	s_cselect_b32 s31, s19, s1
	s_cselect_b32 s30, s51, s0
	v_add_u32_e32 v140, s56, v144
	s_cselect_b32 s29, s17, s54
	s_cselect_b32 s28, s52, s53
	s_add_i32 s0, 0, 0x14000
	ds_read_b128 v[146:149], v140
	ds_read_b128 v[150:153], v140 offset:1024
	ds_read_b128 v[154:157], v140 offset:2048
	ds_read_b128 v[158:161], v140 offset:3072
	v_add_u32_e32 v140, s0, v144
	ds_read_b128 v[162:165], v140
	ds_read_b128 v[166:169], v140 offset:1024
	ds_read_b128 v[170:173], v140 offset:2048
	ds_read_b128 v[174:177], v140 offset:3072
	s_add_i32 m0, s25, 0xc000
	ds_read_b128 v[178:181], v145
	ds_read_b128 v[182:185], v145 offset:1024
	ds_read_b128 v[192:195], v145 offset:2048
	ds_read_b128 v[196:199], v145 offset:3072
	ds_read_b128 v[200:203], v145 offset:4096
	ds_read_b128 v[204:207], v145 offset:5120
	ds_read_b128 v[208:211], v145 offset:6144
	ds_read_b128 v[212:215], v145 offset:7168
	global_load_lds_dwordx4 v136, s[26:27]
	s_add_i32 m0, s25, 0xe000
	s_nop 0
	global_load_lds_dwordx4 v138, s[26:27]
	s_waitcnt vmcnt(8)
	s_waitcnt lgkmcnt(0)
	s_setprio 1
	s_barrier

	v_mfma_f32_16x16x32_bf16 v[126:129], v[146:149], v[178:181], v[126:129]
	v_mfma_f32_16x16x32_bf16 v[126:129], v[150:153], v[182:185], v[126:129]
	v_mfma_f32_16x16x32_bf16 v[122:125], v[158:161], v[182:185], v[122:125]
	v_mfma_f32_16x16x32_bf16 v[122:125], v[154:157], v[178:181], v[122:125]
	v_mfma_f32_16x16x32_bf16 v[106:109], v[154:157], v[192:195], v[106:109]
	v_mfma_f32_16x16x32_bf16 v[106:109], v[158:161], v[196:199], v[106:109]
	v_mfma_f32_16x16x32_bf16 v[114:117], v[150:153], v[196:199], v[114:117]
	v_mfma_f32_16x16x32_bf16 v[114:117], v[146:149], v[192:195], v[114:117]
	v_mfma_f32_16x16x32_bf16 v[98:101], v[146:149], v[200:203], v[98:101]
	v_mfma_f32_16x16x32_bf16 v[98:101], v[150:153], v[204:207], v[98:101]
	v_mfma_f32_16x16x32_bf16 v[90:93], v[158:161], v[204:207], v[90:93]
	v_mfma_f32_16x16x32_bf16 v[90:93], v[154:157], v[200:203], v[90:93]
	v_mfma_f32_16x16x32_bf16 v[74:77], v[154:157], v[208:211], v[74:77]
	v_mfma_f32_16x16x32_bf16 v[74:77], v[158:161], v[212:215], v[74:77]
	v_mfma_f32_16x16x32_bf16 v[82:85], v[150:153], v[212:215], v[82:85]
	v_mfma_f32_16x16x32_bf16 v[82:85], v[146:149], v[208:211], v[82:85]


	v_mfma_f32_16x16x32_bf16 v[118:121], v[162:165], v[178:181], v[118:121]
	v_mfma_f32_16x16x32_bf16 v[118:121], v[166:169], v[182:185], v[118:121]
	v_mfma_f32_16x16x32_bf16 v[110:113], v[174:177], v[182:185], v[110:113]
	v_mfma_f32_16x16x32_bf16 v[110:113], v[170:173], v[178:181], v[110:113]
	v_mfma_f32_16x16x32_bf16 v[94:97], v[170:173], v[192:195], v[94:97]
	v_mfma_f32_16x16x32_bf16 v[94:97], v[174:177], v[196:199], v[94:97]
	v_mfma_f32_16x16x32_bf16 v[102:105], v[166:169], v[196:199], v[102:105]
	v_mfma_f32_16x16x32_bf16 v[102:105], v[162:165], v[192:195], v[102:105]
	v_mfma_f32_16x16x32_bf16 v[86:89], v[162:165], v[200:203], v[86:89]
	v_mfma_f32_16x16x32_bf16 v[86:89], v[166:169], v[204:207], v[86:89]
	v_mfma_f32_16x16x32_bf16 v[78:81], v[174:177], v[204:207], v[78:81]
	v_mfma_f32_16x16x32_bf16 v[78:81], v[170:173], v[200:203], v[78:81]
	v_mfma_f32_16x16x32_bf16 v[66:69], v[170:173], v[208:211], v[66:69]
	v_mfma_f32_16x16x32_bf16 v[66:69], v[174:177], v[212:215], v[66:69]
	v_mfma_f32_16x16x32_bf16 v[70:73], v[166:169], v[212:215], v[70:73]
	v_mfma_f32_16x16x32_bf16 v[70:73], v[162:165], v[208:211], v[70:73]
	s_barrier
	s_setprio 0
	s_add_i32 s1, s56, s39
	s_mov_b32 m0, s1
	ds_read_b128 v[178:181], v145 offset:16384
	ds_read_b128 v[182:185], v145 offset:17408
	ds_read_b128 v[192:195], v145 offset:18432
	ds_read_b128 v[196:199], v145 offset:19456
	ds_read_b128 v[200:203], v145 offset:20480
	ds_read_b128 v[204:207], v145 offset:21504
	ds_read_b128 v[208:211], v145 offset:22528
	ds_read_b128 v[212:215], v145 offset:23552
	global_load_lds_dwordx4 v186, s[28:29]
	s_add_i32 m0, s1, 0x2000
	s_add_u32 s56, s28, 0x80000
	s_addc_u32 s57, s29, 0
	s_add_i32 s0, s0, s39
	global_load_lds_dwordx4 v130, s[28:29]
	s_mov_b32 m0, s0
	s_nop 0
	global_load_lds_dwordx4 v186, s[56:57]
	s_add_i32 m0, s0, 0x2000
	s_nop 0
	global_load_lds_dwordx4 v130, s[56:57]
	s_mov_b32 m0, s25
	s_nop 0
	global_load_lds_dwordx4 v134, s[30:31]
	s_mov_b32 m0, s40
	s_nop 0
	global_load_lds_dwordx4 v132, s[30:31]
	s_waitcnt vmcnt(8)
	s_waitcnt lgkmcnt(0)
	s_setprio 1
	s_barrier

	v_mfma_f32_16x16x32_bf16 v[62:65], v[146:149], v[178:181], v[62:65]
	v_mfma_f32_16x16x32_bf16 v[62:65], v[150:153], v[182:185], v[62:65]
	v_mfma_f32_16x16x32_bf16 v[58:61], v[158:161], v[182:185], v[58:61]
	v_mfma_f32_16x16x32_bf16 v[58:61], v[154:157], v[178:181], v[58:61]
	v_mfma_f32_16x16x32_bf16 v[42:45], v[154:157], v[192:195], v[42:45]
	v_mfma_f32_16x16x32_bf16 v[42:45], v[158:161], v[196:199], v[42:45]
	v_mfma_f32_16x16x32_bf16 v[50:53], v[150:153], v[196:199], v[50:53]
	v_mfma_f32_16x16x32_bf16 v[50:53], v[146:149], v[192:195], v[50:53]
	v_mfma_f32_16x16x32_bf16 v[34:37], v[146:149], v[200:203], v[34:37]
	v_mfma_f32_16x16x32_bf16 v[34:37], v[150:153], v[204:207], v[34:37]
	v_mfma_f32_16x16x32_bf16 v[26:29], v[158:161], v[204:207], v[26:29]
	v_mfma_f32_16x16x32_bf16 v[26:29], v[154:157], v[200:203], v[26:29]
	v_mfma_f32_16x16x32_bf16 v[10:13], v[154:157], v[208:211], v[10:13]
	v_mfma_f32_16x16x32_bf16 v[10:13], v[158:161], v[212:215], v[10:13]
	v_mfma_f32_16x16x32_bf16 v[18:21], v[150:153], v[212:215], v[18:21]
	v_mfma_f32_16x16x32_bf16 v[18:21], v[146:149], v[208:211], v[18:21]


	v_mfma_f32_16x16x32_bf16 v[54:57], v[162:165], v[178:181], v[54:57]
	v_mfma_f32_16x16x32_bf16 v[54:57], v[166:169], v[182:185], v[54:57]
	v_mfma_f32_16x16x32_bf16 v[46:49], v[174:177], v[182:185], v[46:49]
	v_mfma_f32_16x16x32_bf16 v[46:49], v[170:173], v[178:181], v[46:49]
	v_mfma_f32_16x16x32_bf16 v[30:33], v[170:173], v[192:195], v[30:33]
	v_mfma_f32_16x16x32_bf16 v[30:33], v[174:177], v[196:199], v[30:33]
	v_mfma_f32_16x16x32_bf16 v[38:41], v[166:169], v[196:199], v[38:41]
	v_mfma_f32_16x16x32_bf16 v[38:41], v[162:165], v[192:195], v[38:41]
	v_mfma_f32_16x16x32_bf16 v[22:25], v[162:165], v[200:203], v[22:25]
	v_mfma_f32_16x16x32_bf16 v[22:25], v[166:169], v[204:207], v[22:25]
	v_mfma_f32_16x16x32_bf16 v[14:17], v[174:177], v[204:207], v[14:17]
	v_mfma_f32_16x16x32_bf16 v[14:17], v[170:173], v[200:203], v[14:17]
	v_mfma_f32_16x16x32_bf16 v[2:5], v[170:173], v[208:211], v[2:5]
	v_mfma_f32_16x16x32_bf16 v[2:5], v[174:177], v[212:215], v[2:5]
	v_mfma_f32_16x16x32_bf16 v[6:9], v[166:169], v[212:215], v[6:9]
	v_mfma_f32_16x16x32_bf16 v[6:9], v[162:165], v[208:211], v[6:9]
	s_barrier
	s_setprio 0
	s_add_i32 s0, 0, 0x18000
	s_add_i32 s1, 0, 0x1c000
	v_add_u32_e32 v158, s0, v144
	v_add_u32_e32 v174, s1, v144
	ds_read_b128 v[146:149], v158
	ds_read_b128 v[150:153], v158 offset:1024
	ds_read_b128 v[154:157], v158 offset:2048
	ds_read_b128 v[158:161], v158 offset:3072
	ds_read_b128 v[162:165], v174
	ds_read_b128 v[166:169], v174 offset:1024
	ds_read_b128 v[170:173], v174 offset:2048
	ds_read_b128 v[174:177], v174 offset:3072
	s_add_u32 s30, s30, 0x80000
	s_addc_u32 s31, s31, 0
	s_mov_b32 m0, s41
	ds_read_b128 v[178:181], v145 offset:32768
	ds_read_b128 v[182:185], v145 offset:33792
	ds_read_b128 v[192:195], v145 offset:34816
	ds_read_b128 v[196:199], v145 offset:35840
	ds_read_b128 v[200:203], v145 offset:36864
	ds_read_b128 v[204:207], v145 offset:37888
	ds_read_b128 v[208:211], v145 offset:38912
	ds_read_b128 v[212:215], v145 offset:39936
	global_load_lds_dwordx4 v134, s[30:31]
	s_mov_b32 m0, s42
	s_nop 0
	global_load_lds_dwordx4 v132, s[30:31]
	s_waitcnt vmcnt(8)
	s_waitcnt lgkmcnt(0)
	s_setprio 1
	s_barrier

	v_mfma_f32_16x16x32_bf16 v[126:129], v[146:149], v[178:181], v[126:129]
	v_mfma_f32_16x16x32_bf16 v[126:129], v[150:153], v[182:185], v[126:129]
	v_mfma_f32_16x16x32_bf16 v[122:125], v[158:161], v[182:185], v[122:125]
	v_mfma_f32_16x16x32_bf16 v[122:125], v[154:157], v[178:181], v[122:125]
	v_mfma_f32_16x16x32_bf16 v[106:109], v[154:157], v[192:195], v[106:109]
	v_mfma_f32_16x16x32_bf16 v[106:109], v[158:161], v[196:199], v[106:109]
	v_mfma_f32_16x16x32_bf16 v[114:117], v[150:153], v[196:199], v[114:117]
	v_mfma_f32_16x16x32_bf16 v[114:117], v[146:149], v[192:195], v[114:117]
	v_mfma_f32_16x16x32_bf16 v[98:101], v[146:149], v[200:203], v[98:101]
	v_mfma_f32_16x16x32_bf16 v[98:101], v[150:153], v[204:207], v[98:101]
	v_mfma_f32_16x16x32_bf16 v[90:93], v[158:161], v[204:207], v[90:93]
	v_mfma_f32_16x16x32_bf16 v[90:93], v[154:157], v[200:203], v[90:93]
	v_mfma_f32_16x16x32_bf16 v[74:77], v[154:157], v[208:211], v[74:77]
	v_mfma_f32_16x16x32_bf16 v[74:77], v[158:161], v[212:215], v[74:77]
	v_mfma_f32_16x16x32_bf16 v[82:85], v[150:153], v[212:215], v[82:85]
	v_mfma_f32_16x16x32_bf16 v[82:85], v[146:149], v[208:211], v[82:85]


	v_mfma_f32_16x16x32_bf16 v[118:121], v[162:165], v[178:181], v[118:121]
	v_mfma_f32_16x16x32_bf16 v[118:121], v[166:169], v[182:185], v[118:121]
	v_mfma_f32_16x16x32_bf16 v[110:113], v[174:177], v[182:185], v[110:113]
	v_mfma_f32_16x16x32_bf16 v[110:113], v[170:173], v[178:181], v[110:113]
	v_mfma_f32_16x16x32_bf16 v[94:97], v[170:173], v[192:195], v[94:97]
	v_mfma_f32_16x16x32_bf16 v[94:97], v[174:177], v[196:199], v[94:97]
	v_mfma_f32_16x16x32_bf16 v[102:105], v[166:169], v[196:199], v[102:105]
	v_mfma_f32_16x16x32_bf16 v[102:105], v[162:165], v[192:195], v[102:105]
	v_mfma_f32_16x16x32_bf16 v[86:89], v[162:165], v[200:203], v[86:89]
	v_mfma_f32_16x16x32_bf16 v[86:89], v[166:169], v[204:207], v[86:89]
	v_mfma_f32_16x16x32_bf16 v[78:81], v[174:177], v[204:207], v[78:81]
	v_mfma_f32_16x16x32_bf16 v[78:81], v[170:173], v[200:203], v[78:81]
	v_mfma_f32_16x16x32_bf16 v[66:69], v[170:173], v[208:211], v[66:69]
	v_mfma_f32_16x16x32_bf16 v[66:69], v[174:177], v[212:215], v[66:69]
	v_mfma_f32_16x16x32_bf16 v[70:73], v[166:169], v[212:215], v[70:73]
	v_mfma_f32_16x16x32_bf16 v[70:73], v[162:165], v[208:211], v[70:73]
	s_barrier
	s_setprio 0
	s_add_i32 s0, s0, s39
	s_mov_b32 m0, s0
	ds_read_b128 v[178:181], v145 offset:49152
	ds_read_b128 v[182:185], v145 offset:50176
	ds_read_b128 v[192:195], v145 offset:51200
	ds_read_b128 v[196:199], v145 offset:52224
	ds_read_b128 v[200:203], v145 offset:53248
	ds_read_b128 v[204:207], v145 offset:54272
	ds_read_b128 v[208:211], v145 offset:55296
	ds_read_b128 v[212:215], v145 offset:56320
	s_add_u32 s100, s28, 0x80
	s_addc_u32 s101, s29, 0
	global_load_lds_dwordx4 v186, s[100:101]
	s_add_i32 m0, s0, 0x2000
	s_add_u32 s28, s28, 0x80080
	s_addc_u32 s29, s29, 0
	s_add_i32 s0, s1, s39
	s_add_u32 s100, s28, 0xfff80000
	s_addc_u32 s101, s29, -1
	global_load_lds_dwordx4 v130, s[100:101]
	s_mov_b32 m0, s0
	s_nop 0
	global_load_lds_dwordx4 v186, s[28:29]
	s_add_i32 m0, s0, 0x2000
	s_nop 0
	global_load_lds_dwordx4 v130, s[28:29]
	s_mov_b32 m0, s43
	s_nop 0
	s_add_u32 s100, s30, 0xfff80080
	s_addc_u32 s101, s31, -1
	global_load_lds_dwordx4 v134, s[100:101]
	s_mov_b32 m0, s44
	s_nop 0
	s_add_u32 s100, s30, 0xfff80080
	s_addc_u32 s101, s31, -1
	global_load_lds_dwordx4 v132, s[100:101]
	s_waitcnt vmcnt(8)
	s_waitcnt lgkmcnt(0)
	s_setprio 1
	s_barrier

	v_mfma_f32_16x16x32_bf16 v[62:65], v[146:149], v[178:181], v[62:65]
	v_mfma_f32_16x16x32_bf16 v[62:65], v[150:153], v[182:185], v[62:65]
	v_mfma_f32_16x16x32_bf16 v[58:61], v[158:161], v[182:185], v[58:61]
	v_mfma_f32_16x16x32_bf16 v[58:61], v[154:157], v[178:181], v[58:61]
	v_mfma_f32_16x16x32_bf16 v[42:45], v[154:157], v[192:195], v[42:45]
	v_mfma_f32_16x16x32_bf16 v[42:45], v[158:161], v[196:199], v[42:45]
	v_mfma_f32_16x16x32_bf16 v[50:53], v[150:153], v[196:199], v[50:53]
	v_mfma_f32_16x16x32_bf16 v[50:53], v[146:149], v[192:195], v[50:53]
	v_mfma_f32_16x16x32_bf16 v[34:37], v[146:149], v[200:203], v[34:37]
	v_mfma_f32_16x16x32_bf16 v[34:37], v[150:153], v[204:207], v[34:37]
	v_mfma_f32_16x16x32_bf16 v[26:29], v[158:161], v[204:207], v[26:29]
	v_mfma_f32_16x16x32_bf16 v[26:29], v[154:157], v[200:203], v[26:29]
	v_mfma_f32_16x16x32_bf16 v[10:13], v[154:157], v[208:211], v[10:13]
	v_mfma_f32_16x16x32_bf16 v[10:13], v[158:161], v[212:215], v[10:13]
	v_mfma_f32_16x16x32_bf16 v[18:21], v[150:153], v[212:215], v[18:21]
	v_mfma_f32_16x16x32_bf16 v[18:21], v[146:149], v[208:211], v[18:21]


	v_mfma_f32_16x16x32_bf16 v[54:57], v[162:165], v[178:181], v[54:57]
	v_mfma_f32_16x16x32_bf16 v[54:57], v[166:169], v[182:185], v[54:57]
	v_mfma_f32_16x16x32_bf16 v[46:49], v[174:177], v[182:185], v[46:49]
	v_mfma_f32_16x16x32_bf16 v[46:49], v[170:173], v[178:181], v[46:49]
	v_mfma_f32_16x16x32_bf16 v[30:33], v[170:173], v[192:195], v[30:33]
	v_mfma_f32_16x16x32_bf16 v[30:33], v[174:177], v[196:199], v[30:33]
	v_mfma_f32_16x16x32_bf16 v[38:41], v[166:169], v[196:199], v[38:41]
	v_mfma_f32_16x16x32_bf16 v[38:41], v[162:165], v[192:195], v[38:41]
	v_mfma_f32_16x16x32_bf16 v[22:25], v[162:165], v[200:203], v[22:25]
	v_mfma_f32_16x16x32_bf16 v[22:25], v[166:169], v[204:207], v[22:25]
	v_mfma_f32_16x16x32_bf16 v[14:17], v[174:177], v[204:207], v[14:17]
	v_mfma_f32_16x16x32_bf16 v[14:17], v[170:173], v[200:203], v[14:17]
	v_mfma_f32_16x16x32_bf16 v[2:5], v[170:173], v[208:211], v[2:5]
	v_mfma_f32_16x16x32_bf16 v[2:5], v[174:177], v[212:215], v[2:5]
	v_mfma_f32_16x16x32_bf16 v[6:9], v[166:169], v[212:215], v[6:9]
	v_mfma_f32_16x16x32_bf16 v[6:9], v[162:165], v[208:211], v[6:9]
	s_barrier
	s_setprio 0
	s_add_i32 s55, s55, 2
	s_add_u32 s26, s26, 0x100
	s_addc_u32 s27, s27, 0
	s_add_u32 s53, s53, 0x100
	s_addc_u32 s54, s54, 0
	s_cmp_gt_u32 s55, 29
	s_cbranch_scc0 .LBB0_443
	s_and_b64 vcc, exec, s[14:15]
	s_cbranch_vccz .LBB0_446
	s_barrier
